# mla_fin: waves alternate q and kv items each iteration (flip the role mask) to balance the heavier kv items across all 8 waves
# baseline (speedup 1.0000x reference)
; DI unsigned cvtpk(float lo, float hi) { f32x2_t v = {lo, hi}; bf16x2_t b = __builtin_convertvector(v, bf16x2_t); return __builtin_bit_cast(unsigned, b); }
; DI void phase_mla_fin(ArgsP a, int tb_, int l, char* shm, int vcu, int G) {
;     ...
;     for (int it = gw; it < (M / 8) * 2; it += NGW) {
;         const int m = (it >> 1) * 8 + (lane >> 3), h = lane & 7;
;     ...
; #pragma unroll
;             for (int i = 0; i < 4; ++i) { u32x4 ow; ow.x = cvtpk(xr[8 * i], xr[8 * i + 1]); ow.y = cvtpk(xr[8 * i + 2], xr[8 * i + 3]); ow.z = cvtpk(xr[8 * i + 4], xr[8 * i + 5]); ow.w = cvtpk(xr[8 * i + 6], xr[8 * i + 7]); o[8 + i] = ow; }
.LBB0_964:
	s_or_b64 exec, exec, s[30:31]
	s_not_b64 vcc, vcc
	s_waitcnt lgkmcnt(0)
	v_cvt_pk_bf16_f32 v0, v58, v59
	v_cvt_pk_bf16_f32 v1, v34, v35
	v_cvt_pk_bf16_f32 v2, v76, v77
	v_cvt_pk_bf16_f32 v3, v38, v39
	global_store_dwordx4 v[68:69], v[0:3], off offset:128
	v_add_u32_e32 v168, s27, v168
	s_movk_i32 s0, 0x21ff
	v_cvt_pk_bf16_f32 v0, v64, v65
	v_cvt_pk_bf16_f32 v1, v74, v75
	v_cvt_pk_bf16_f32 v2, v78, v79
	v_cvt_pk_bf16_f32 v3, v80, v81
	global_store_dwordx4 v[68:69], v[0:3], off offset:144
	v_cmp_lt_i32_e64 s[6:7], s0, v168
	s_or_b64 s[28:29], s[6:7], s[28:29]
	v_cvt_pk_bf16_f32 v0, v36, v37
	v_cvt_pk_bf16_f32 v1, v32, v33
	v_cvt_pk_bf16_f32 v2, v44, v45
	v_cvt_pk_bf16_f32 v3, v50, v51
	global_store_dwordx4 v[68:69], v[0:3], off offset:160
	v_add_u32_e32 v174, s36, v174
	s_nop 0
	v_cvt_pk_bf16_f32 v0, v66, v67
	v_cvt_pk_bf16_f32 v1, v42, v43
	v_cvt_pk_bf16_f32 v2, v48, v49
	v_cvt_pk_bf16_f32 v3, v40, v41
	global_store_dwordx4 v[68:69], v[0:3], off offset:176
	s_andn2_b64 exec, exec, s[28:29]
	s_cbranch_execz .LBB0_969
